# v40 plus XCD-aware n-tile rotation in the GEMM tile loop: nt rotated by (mt*ntiles)&7 so each XCD keeps a fixed subset of weight n-tiles resident in its L2
# speedup vs baseline: 1.0464x; 1.0086x over previous
; template <bool MERGE>
; DI void gemm_phase(const GemmDesc& d, const Params& P, char* lds) {
;     ...
;   for (int t = blockIdx.x; t < ntl; t += gridDim.x) {
;     int mt = t / d.ntiles;
;     int nt = t - mt * d.ntiles;
;     if (d.ntiles == 8) {
;       const int m4 = d.mtiles & ~3;
;       if (t < 8 * m4) {
;         const int x = t & 7, k = t >> 3;
;         nt = 4 * (x & 1) + (k & 3);
;         mt = 4 * (k >> 2) + (x >> 1);
;       }
;     }
;     if (d.skipctx && mt >= 128) mt += 2;
;     const u16* A = d.A; const u16* W = d.W; int lda = d.lda, K = d.K;
;     bool trans = false;
;     int uq = 0;
;     if (d.epi == EPI_PROJ) {
.LBB0_453:
	s_ashr_i32 s1, s20, 31
	s_xor_b32 s0, s0, s1
	s_sub_i32 s2, s0, s1
	s_mul_i32 s0, s2, s57
	s_sub_i32 s6, s20, s0
	s_and_b32 s100, s0, 7
	s_add_i32 s6, s6, s100
	s_cmp_ge_i32 s6, s57
	s_cselect_b32 s100, s57, 0
	s_sub_i32 s6, s6, s100
	s_nop 0
	s_cmp_lt_i32 s56, 3
	s_mov_b64 s[4:5], -1
	s_cbranch_scc1 .LBB0_457

; __global__ void __launch_bounds__(256, 2) fwd_megakernel(Params P) {
	.amdhsa_kernel _Z14fwd_megakernel6Params
		.amdhsa_group_segment_fixed_size 0
		.amdhsa_private_segment_fixed_size 0
		.amdhsa_kernarg_size 504
		.amdhsa_user_sgpr_count 2
		.amdhsa_user_sgpr_dispatch_ptr 0
		.amdhsa_user_sgpr_queue_ptr 0
		.amdhsa_user_sgpr_kernarg_segment_ptr 1
		.amdhsa_user_sgpr_dispatch_id 0
		.amdhsa_user_sgpr_kernarg_preload_length 0
		.amdhsa_user_sgpr_kernarg_preload_offset 0
		.amdhsa_user_sgpr_private_segment_size 0
		.amdhsa_uses_dynamic_stack 0
		.amdhsa_enable_private_segment 0
		.amdhsa_system_sgpr_workgroup_id_x 1
		.amdhsa_system_sgpr_workgroup_id_y 0
		.amdhsa_system_sgpr_workgroup_id_z 0
		.amdhsa_system_sgpr_workgroup_info 0
		.amdhsa_system_vgpr_workitem_id 2
		.amdhsa_next_free_vgpr 256
		.amdhsa_next_free_sgpr 102
		.amdhsa_accum_offset 256
		.amdhsa_reserve_vcc 1
		.amdhsa_float_round_mode_32 0
		.amdhsa_float_round_mode_16_64 0
		.amdhsa_float_denorm_mode_32 3
		.amdhsa_float_denorm_mode_16_64 3
		.amdhsa_dx10_clamp 1
		.amdhsa_ieee_mode 1
		.amdhsa_fp16_overflow 0
		.amdhsa_tg_split 0
		.amdhsa_exception_fp_ieee_invalid_op 0
		.amdhsa_exception_fp_denorm_src 0
		.amdhsa_exception_fp_ieee_div_zero 0
		.amdhsa_exception_fp_ieee_overflow 0
		.amdhsa_exception_fp_ieee_underflow 0
		.amdhsa_exception_fp_ieee_inexact 0
		.amdhsa_exception_int_div_zero 0
	.end_amdhsa_kernel

; __global__ void __launch_bounds__(256, 2) fwd_megakernel(Params P) {
amdhsa.kernels:
  - .agpr_count:     0
    .args:
      - .offset:         0
        .size:           248
        .value_kind:     by_value
      - .offset:         248
        .size:           4
        .value_kind:     hidden_block_count_x
      - .offset:         252
        .size:           4
        .value_kind:     hidden_block_count_y
      - .offset:         256
        .size:           4
        .value_kind:     hidden_block_count_z
      - .offset:         260
        .size:           2
        .value_kind:     hidden_group_size_x
      - .offset:         262
        .size:           2
        .value_kind:     hidden_group_size_y
      - .offset:         264
        .size:           2
        .value_kind:     hidden_group_size_z
      - .offset:         266
        .size:           2
        .value_kind:     hidden_remainder_x
      - .offset:         268
        .size:           2
        .value_kind:     hidden_remainder_y
      - .offset:         270
        .size:           2
        .value_kind:     hidden_remainder_z
      - .offset:         288
        .size:           8
        .value_kind:     hidden_global_offset_x
      - .offset:         296
        .size:           8
        .value_kind:     hidden_global_offset_y
      - .offset:         304
        .size:           8
        .value_kind:     hidden_global_offset_z
      - .offset:         312
        .size:           2
        .value_kind:     hidden_grid_dims
      - .offset:         336
        .size:           8
        .value_kind:     hidden_multigrid_sync_arg
      - .offset:         368
        .size:           4
        .value_kind:     hidden_dynamic_lds_size
    .group_segment_fixed_size: 0
    .kernarg_segment_align: 8
    .kernarg_segment_size: 504
    .language:       OpenCL C
    .language_version:
      - 2
      - 0
    .max_flat_workgroup_size: 256
    .name:           _Z14fwd_megakernel6Params
    .private_segment_fixed_size: 0
    .sgpr_count:     108
    .sgpr_spill_count: 552
    .symbol:         _Z14fwd_megakernel6Params.kd
    .uniform_work_group_size: 1
    .uses_dynamic_stack: false
    .vgpr_count:     256
    .vgpr_spill_count: 0
    .wavefront_size: 64
